# speedup vs baseline: 1.0035x; 1.0035x over previous
; #define PG8_STAGE(bufoff, gbase, voff) do { _Pragma("unroll") for (int _i = 0; _i < 2; ++_i) \
;         __builtin_amdgcn_global_load_lds((const unsigned*)((const char*)(gbase) + (voff)[_i]), (LAS unsigned*)(lds + (bufoff) + ldsw + _i * 8192), 16, 0, 0); } while (0)
; #define PG8_LDA(dst, b, h) do { _Pragma("unroll") for (int m = 0; m < 4; ++m) _Pragma("unroll") for (int k = 0; k < 2; ++k) dst[m][k] = *(const LAS bf16x8*)(lds + PG8_SA(b, h) + aoff + m * 2048 + k * 1024); } while (0)
; #define PG8_LDB(dst, b, h) do { _Pragma("unroll") for (int n = 0; n < 2; ++n) _Pragma("unroll") for (int k = 0; k < 2; ++k) dst[n][k] = *(const LAS bf16x8*)(lds + PG8_SB(b, h) + boff + n * 2048 + k * 1024); } while (0)
; #define PG8_MMA(ai, bj, At, Bt) do { __builtin_amdgcn_s_setprio(1); _Pragma("unroll") for (int m = 0; m < 4; ++m) _Pragma("unroll") for (int n = 0; n < 2; ++n) _Pragma("unroll") for (int k = 0; k < 2; ++k) \
;         acc[ai][bj][m][n] = __builtin_amdgcn_mfma_f32_16x16x32_bf16(Bt[n][k], At[m][k], acc[ai][bj][m][n], 0, 0, 0); __builtin_amdgcn_s_setprio(0); } while (0)
; #define PG8_WAIT_V(n) asm volatile("s_waitcnt vmcnt(" #n ")" ::: "memory")
; #define PG8_WAIT_L(n) asm volatile("s_waitcnt lgkmcnt(" #n ")" ::: "memory")
; #define PG8_BAR __builtin_amdgcn_s_barrier()
; __device__ __forceinline__ void gemm_phase(LAS unsigned char* lds, const Gemm g, const StaticOrder& S, const EpiAny& EA) {
;     ...
;         for (int t = 0; t < nt; t += 2) {
;             const bool last = (t == nt - 2);
;             const char* a1 = cA + (size_t)(t + 1) * kstep;
;             const char* a2 = last ? nA : cA + (size_t)(t + 2) * kstep; const char* b2 = last ? nB : cB + (size_t)(t + 2) * kstep;
;             const char* a3 = a2 + kstep; const char* b3 = b2 + kstep;
;             PG8_LDB(B0, 0, 0); PG8_SCHED; PG8_LDA(At, 0, 0); PG8_STAGE(PG8_SA(1, 1), a1 + hstep, voffA);
;             PG8_WAIT_L(8); PG8_BAR; PG8_WAIT_L(0); PG8_MMA(0, 0, At, B0); PG8_BAR; PG8_SCHED;
;             PG8_LDB(B1, 0, 1); PG8_STAGE(PG8_SB(0, 0), b2, voffB);
;             PG8_BAR; PG8_WAIT_L(0); PG8_MMA(0, 1, At, B1); PG8_BAR;
;             PG8_LDA(At, 0, 1); PG8_STAGE(PG8_SA(0, 0), a2, voffA);
;             PG8_BAR; PG8_WAIT_L(0); PG8_MMA(1, 0, At, B0); PG8_BAR; PG8_SCHED;
;             PG8_STAGE(PG8_SB(0, 1), b2 + hstep, voffB);
;             PG8_WAIT_V(6); PG8_BAR; PG8_MMA(1, 1, At, B1); PG8_BAR;
.LBB0_498:
	s_mov_b32 s12, 0
	s_mov_b64 s[0:1], 0x100
	v_mov_b64_e32 v[130:131], v[204:205]
	s_waitcnt lgkmcnt(0)
	v_mov_b64_e32 v[132:133], v[202:203]
	s_add_i32 s13, s12, 2
	s_add_u32 s24, s70, s0
	s_addc_u32 s25, s71, s1
	s_add_u32 s44, s28, s0
	s_addc_u32 s45, s29, s1
	s_add_i32 s46, 0, 0x10000
	v_add_u32_e32 v0, s46, v228
.LBB0_499:
	ds_read_b128 v[134:137], v0
	ds_read_b128 v[138:141], v0 offset:1024
	ds_read_b128 v[142:145], v0 offset:2048
	ds_read_b128 v[146:149], v0 offset:3072
	s_cmp_eq_u32 s82, s12
	s_cselect_b32 s37, s51, s25
	s_cselect_b32 s36, s50, s24
	s_cselect_b32 s45, s69, s45
	s_cselect_b32 s44, s68, s44
	v_lshl_add_u64 v[182:183], s[70:71], 0, v[132:133]
	s_add_i32 m0, s73, 0xc000
	ds_read_b128 v[150:153], v234
	ds_read_b128 v[154:157], v234 offset:1024
	ds_read_b128 v[158:161], v234 offset:2048
	ds_read_b128 v[162:165], v234 offset:3072
	ds_read_b128 v[166:169], v234 offset:4096
	ds_read_b128 v[170:173], v234 offset:5120
	ds_read_b128 v[174:177], v234 offset:6144
	ds_read_b128 v[178:181], v234 offset:7168
	global_load_lds_dwordx4 v[182:183], off
	v_lshl_add_u64 v[182:183], s[70:71], 0, v[130:131]
	s_add_i32 m0, s73, 0xe000
	s_nop 0
	global_load_lds_dwordx4 v[182:183], off
	s_waitcnt lgkmcnt(8)
	s_barrier
	s_waitcnt lgkmcnt(0)
	s_setprio 1
	s_waitcnt lgkmcnt(0)
	v_mfma_f32_16x16x32_bf16 v[126:129], v[134:137], v[150:153], v[126:129]
	v_mfma_f32_16x16x32_bf16 v[122:125], v[142:145], v[150:153], v[122:125]
	v_mfma_f32_16x16x32_bf16 v[118:121], v[134:137], v[158:161], v[118:121]
	v_mfma_f32_16x16x32_bf16 v[114:117], v[142:145], v[158:161], v[114:117]
	v_mfma_f32_16x16x32_bf16 v[110:113], v[134:137], v[166:169], v[110:113]
	v_mfma_f32_16x16x32_bf16 v[106:109], v[142:145], v[166:169], v[106:109]
	v_mfma_f32_16x16x32_bf16 v[102:105], v[134:137], v[174:177], v[102:105]
	v_mfma_f32_16x16x32_bf16 v[98:101], v[142:145], v[174:177], v[98:101]
	v_mfma_f32_16x16x32_bf16 v[126:129], v[138:141], v[154:157], v[126:129]
	v_mfma_f32_16x16x32_bf16 v[122:125], v[146:149], v[154:157], v[122:125]
	v_mfma_f32_16x16x32_bf16 v[118:121], v[138:141], v[162:165], v[118:121]
	v_mfma_f32_16x16x32_bf16 v[114:117], v[146:149], v[162:165], v[114:117]
	v_mfma_f32_16x16x32_bf16 v[110:113], v[138:141], v[170:173], v[110:113]
	v_mfma_f32_16x16x32_bf16 v[106:109], v[146:149], v[170:173], v[106:109]
	v_mfma_f32_16x16x32_bf16 v[102:105], v[138:141], v[178:181], v[102:105]
	v_mfma_f32_16x16x32_bf16 v[98:101], v[146:149], v[178:181], v[98:101]
	s_setprio 0
	s_barrier
	s_add_i32 s12, 0, 0x14000
	s_add_i32 s24, s46, s65
	v_add_u32_e32 v0, s12, v228
	v_lshl_add_u64 v[186:187], s[44:45], 0, v[194:195]
	s_mov_b32 m0, s24
	ds_read_b128 v[182:185], v0
	ds_read_b128 v[206:209], v0 offset:1024
	ds_read_b128 v[210:213], v0 offset:2048
	ds_read_b128 v[214:217], v0 offset:3072
	global_load_lds_dwordx4 v[186:187], off
	v_lshl_add_u64 v[218:219], s[44:45], 0, v[190:191]
	s_add_i32 m0, s24, 0x2000
	s_nop 0
	global_load_lds_dwordx4 v[218:219], off
	s_barrier
	s_waitcnt lgkmcnt(0)
	s_setprio 1
	s_waitcnt lgkmcnt(0)
	v_mfma_f32_16x16x32_bf16 v[94:97], v[182:185], v[150:153], v[94:97]
	v_mfma_f32_16x16x32_bf16 v[90:93], v[210:213], v[150:153], v[90:93]
	v_mfma_f32_16x16x32_bf16 v[86:89], v[182:185], v[158:161], v[86:89]
	v_mfma_f32_16x16x32_bf16 v[82:85], v[210:213], v[158:161], v[82:85]
	v_mfma_f32_16x16x32_bf16 v[78:81], v[182:185], v[166:169], v[78:81]
	v_mfma_f32_16x16x32_bf16 v[74:77], v[210:213], v[166:169], v[74:77]
	v_mfma_f32_16x16x32_bf16 v[70:73], v[182:185], v[174:177], v[70:73]
	v_mfma_f32_16x16x32_bf16 v[66:69], v[210:213], v[174:177], v[66:69]
	v_mfma_f32_16x16x32_bf16 v[94:97], v[206:209], v[154:157], v[94:97]
	v_mfma_f32_16x16x32_bf16 v[90:93], v[214:217], v[154:157], v[90:93]
	v_mfma_f32_16x16x32_bf16 v[86:89], v[206:209], v[162:165], v[86:89]
	v_mfma_f32_16x16x32_bf16 v[82:85], v[214:217], v[162:165], v[82:85]
	v_mfma_f32_16x16x32_bf16 v[78:81], v[206:209], v[170:173], v[78:81]
	v_mfma_f32_16x16x32_bf16 v[74:77], v[214:217], v[170:173], v[74:77]
	v_mfma_f32_16x16x32_bf16 v[70:73], v[206:209], v[178:181], v[70:73]
	v_mfma_f32_16x16x32_bf16 v[66:69], v[214:217], v[178:181], v[66:69]
	s_setprio 0
	s_mov_b32 m0, s73
	v_lshl_add_u64 v[220:221], s[36:37], 0, v[192:193]
	s_barrier
	ds_read_b128 v[150:153], v234 offset:16384
	ds_read_b128 v[154:157], v234 offset:17408
	ds_read_b128 v[158:161], v234 offset:18432
	ds_read_b128 v[162:165], v234 offset:19456
	ds_read_b128 v[166:169], v234 offset:20480
	ds_read_b128 v[170:173], v234 offset:21504
	ds_read_b128 v[174:177], v234 offset:22528
	ds_read_b128 v[178:181], v234 offset:23552
	global_load_lds_dwordx4 v[220:221], off
	v_lshl_add_u64 v[222:223], s[36:37], 0, v[188:189]
	s_mov_b32 m0, s18
	s_nop 0
	global_load_lds_dwordx4 v[222:223], off
	s_barrier
	s_waitcnt lgkmcnt(0)
	s_setprio 1
	s_waitcnt lgkmcnt(0)
	v_mfma_f32_16x16x32_bf16 v[62:65], v[134:137], v[150:153], v[62:65]
	v_mfma_f32_16x16x32_bf16 v[58:61], v[142:145], v[150:153], v[58:61]
	v_mfma_f32_16x16x32_bf16 v[54:57], v[134:137], v[158:161], v[54:57]
	v_mfma_f32_16x16x32_bf16 v[50:53], v[142:145], v[158:161], v[50:53]
	v_mfma_f32_16x16x32_bf16 v[46:49], v[134:137], v[166:169], v[46:49]
	v_mfma_f32_16x16x32_bf16 v[42:45], v[142:145], v[166:169], v[42:45]
	v_mfma_f32_16x16x32_bf16 v[38:41], v[134:137], v[174:177], v[38:41]
	v_mfma_f32_16x16x32_bf16 v[34:37], v[142:145], v[174:177], v[34:37]
	v_mfma_f32_16x16x32_bf16 v[62:65], v[138:141], v[154:157], v[62:65]
	v_mfma_f32_16x16x32_bf16 v[58:61], v[146:149], v[154:157], v[58:61]
	v_mfma_f32_16x16x32_bf16 v[54:57], v[138:141], v[162:165], v[54:57]
	v_mfma_f32_16x16x32_bf16 v[50:53], v[146:149], v[162:165], v[50:53]
	v_mfma_f32_16x16x32_bf16 v[46:49], v[138:141], v[170:173], v[46:49]
	v_mfma_f32_16x16x32_bf16 v[42:45], v[146:149], v[170:173], v[42:45]
	v_mfma_f32_16x16x32_bf16 v[38:41], v[138:141], v[178:181], v[38:41]
	v_mfma_f32_16x16x32_bf16 v[34:37], v[146:149], v[178:181], v[34:37]
	s_setprio 0
	s_barrier
; #define PG8_STAGE(bufoff, gbase, voff) do { _Pragma("unroll") for (int _i = 0; _i < 2; ++_i) \
;         __builtin_amdgcn_global_load_lds((const unsigned*)((const char*)(gbase) + (voff)[_i]), (LAS unsigned*)(lds + (bufoff) + ldsw + _i * 8192), 16, 0, 0); } while (0)
; #define PG8_LDA(dst, b, h) do { _Pragma("unroll") for (int m = 0; m < 4; ++m) _Pragma("unroll") for (int k = 0; k < 2; ++k) dst[m][k] = *(const LAS bf16x8*)(lds + PG8_SA(b, h) + aoff + m * 2048 + k * 1024); } while (0)
; #define PG8_LDB(dst, b, h) do { _Pragma("unroll") for (int n = 0; n < 2; ++n) _Pragma("unroll") for (int k = 0; k < 2; ++k) dst[n][k] = *(const LAS bf16x8*)(lds + PG8_SB(b, h) + boff + n * 2048 + k * 1024); } while (0)
; #define PG8_MMA(ai, bj, At, Bt) do { __builtin_amdgcn_s_setprio(1); _Pragma("unroll") for (int m = 0; m < 4; ++m) _Pragma("unroll") for (int n = 0; n < 2; ++n) _Pragma("unroll") for (int k = 0; k < 2; ++k) \
;         acc[ai][bj][m][n] = __builtin_amdgcn_mfma_f32_16x16x32_bf16(Bt[n][k], At[m][k], acc[ai][bj][m][n], 0, 0, 0); __builtin_amdgcn_s_setprio(0); } while (0)
; #define PG8_WAIT_V(n) asm volatile("s_waitcnt vmcnt(" #n ")" ::: "memory")
; #define PG8_WAIT_L(n) asm volatile("s_waitcnt lgkmcnt(" #n ")" ::: "memory")
; #define PG8_BAR __builtin_amdgcn_s_barrier()
; #define PG8_SCHED __builtin_amdgcn_sched_barrier(0)
; __device__ __forceinline__ void gemm_phase(LAS unsigned char* lds, const Gemm g, const StaticOrder& S, const EpiAny& EA) {
;     ...
;             PG8_STAGE(PG8_SB(0, 1), b2 + hstep, voffB);
;             PG8_WAIT_V(6); PG8_BAR; PG8_MMA(1, 1, At, B1); PG8_BAR;
;             PG8_LDB(B0, 1, 0); PG8_SCHED; PG8_LDA(At, 1, 0); PG8_STAGE(PG8_SA(0, 1), a2 + hstep, voffA);
;             PG8_WAIT_L(8); PG8_BAR; PG8_WAIT_L(0); PG8_MMA(0, 0, At, B0); PG8_BAR; PG8_SCHED;
;             PG8_LDB(B1, 1, 1); PG8_STAGE(PG8_SB(1, 0), b3, voffB);
;             PG8_BAR; PG8_WAIT_L(0); PG8_MMA(0, 1, At, B1); PG8_BAR;
;             PG8_LDA(At, 1, 1); PG8_STAGE(PG8_SA(1, 0), a3, voffA);
	s_add_u32 s24, s44, s64
	s_addc_u32 s25, s45, 0
	s_add_i32 s12, s12, s65
	v_lshl_add_u64 v[224:225], s[24:25], 0, v[194:195]
	s_mov_b32 m0, s12
	v_lshl_add_u64 v[238:239], s[24:25], 0, v[190:191]
	global_load_lds_dwordx4 v[224:225], off
	s_add_i32 m0, s12, 0x2000
	s_nop 0
	global_load_lds_dwordx4 v[238:239], off
	s_waitcnt vmcnt(6)
	s_barrier
	s_setprio 1
	v_mfma_f32_16x16x32_bf16 v[30:33], v[182:185], v[150:153], v[30:33]
	v_mfma_f32_16x16x32_bf16 v[26:29], v[210:213], v[150:153], v[26:29]
	v_mfma_f32_16x16x32_bf16 v[22:25], v[182:185], v[158:161], v[22:25]
	v_mfma_f32_16x16x32_bf16 v[18:21], v[210:213], v[158:161], v[18:21]
	v_mfma_f32_16x16x32_bf16 v[14:17], v[182:185], v[166:169], v[14:17]
	v_mfma_f32_16x16x32_bf16 v[10:13], v[210:213], v[166:169], v[10:13]
	v_mfma_f32_16x16x32_bf16 v[6:9], v[182:185], v[174:177], v[6:9]
	v_mfma_f32_16x16x32_bf16 v[2:5], v[210:213], v[174:177], v[2:5]
	v_mfma_f32_16x16x32_bf16 v[30:33], v[206:209], v[154:157], v[30:33]
	v_mfma_f32_16x16x32_bf16 v[26:29], v[214:217], v[154:157], v[26:29]
	v_mfma_f32_16x16x32_bf16 v[22:25], v[206:209], v[162:165], v[22:25]
	v_mfma_f32_16x16x32_bf16 v[18:21], v[214:217], v[162:165], v[18:21]
	v_mfma_f32_16x16x32_bf16 v[14:17], v[206:209], v[170:173], v[14:17]
	v_mfma_f32_16x16x32_bf16 v[10:13], v[214:217], v[170:173], v[10:13]
	v_mfma_f32_16x16x32_bf16 v[6:9], v[206:209], v[178:181], v[6:9]
	v_mfma_f32_16x16x32_bf16 v[2:5], v[214:217], v[178:181], v[2:5]
	s_setprio 0
	s_add_i32 s12, 0, 0x18000
	v_add_u32_e32 v0, s12, v228
	s_barrier
	ds_read_b128 v[134:137], v0
	ds_read_b128 v[138:141], v0 offset:1024
	ds_read_b128 v[142:145], v0 offset:2048
	ds_read_b128 v[146:149], v0 offset:3072
	s_add_u32 s24, s36, s64
	s_addc_u32 s25, s37, 0
	s_mov_b32 m0, s76
	v_lshl_add_u64 v[182:183], s[24:25], 0, v[192:193]
	ds_read_b128 v[150:153], v234 offset:32768
	ds_read_b128 v[154:157], v234 offset:33792
	ds_read_b128 v[158:161], v234 offset:34816
	ds_read_b128 v[162:165], v234 offset:35840
	ds_read_b128 v[166:169], v234 offset:36864
	ds_read_b128 v[170:173], v234 offset:37888
	ds_read_b128 v[174:177], v234 offset:38912
	ds_read_b128 v[178:181], v234 offset:39936
	global_load_lds_dwordx4 v[182:183], off
	v_lshl_add_u64 v[182:183], s[24:25], 0, v[188:189]
	s_mov_b32 m0, s77
	s_nop 0
	global_load_lds_dwordx4 v[182:183], off
	s_waitcnt lgkmcnt(8)
	s_barrier
	s_waitcnt lgkmcnt(0)
	s_setprio 1
	s_waitcnt lgkmcnt(0)
	v_mfma_f32_16x16x32_bf16 v[126:129], v[134:137], v[150:153], v[126:129]
	v_mfma_f32_16x16x32_bf16 v[122:125], v[142:145], v[150:153], v[122:125]
	v_mfma_f32_16x16x32_bf16 v[118:121], v[134:137], v[158:161], v[118:121]
	v_mfma_f32_16x16x32_bf16 v[114:117], v[142:145], v[158:161], v[114:117]
	v_mfma_f32_16x16x32_bf16 v[110:113], v[134:137], v[166:169], v[110:113]
	v_mfma_f32_16x16x32_bf16 v[106:109], v[142:145], v[166:169], v[106:109]
	v_mfma_f32_16x16x32_bf16 v[102:105], v[134:137], v[174:177], v[102:105]
	v_mfma_f32_16x16x32_bf16 v[98:101], v[142:145], v[174:177], v[98:101]
	v_mfma_f32_16x16x32_bf16 v[126:129], v[138:141], v[154:157], v[126:129]
	v_mfma_f32_16x16x32_bf16 v[122:125], v[146:149], v[154:157], v[122:125]
	v_mfma_f32_16x16x32_bf16 v[118:121], v[138:141], v[162:165], v[118:121]
	v_mfma_f32_16x16x32_bf16 v[114:117], v[146:149], v[162:165], v[114:117]
	v_mfma_f32_16x16x32_bf16 v[110:113], v[138:141], v[170:173], v[110:113]
	v_mfma_f32_16x16x32_bf16 v[106:109], v[146:149], v[170:173], v[106:109]
	v_mfma_f32_16x16x32_bf16 v[102:105], v[138:141], v[178:181], v[102:105]
	v_mfma_f32_16x16x32_bf16 v[98:101], v[146:149], v[178:181], v[98:101]
	s_setprio 0
	s_barrier
	s_add_i32 s24, 0, 0x1c000
	s_add_i32 s12, s12, s65
	v_add_u32_e32 v0, s24, v228
	v_lshl_add_u64 v[186:187], v[186:187], 0, s[30:31]
	s_mov_b32 m0, s12
	ds_read_b128 v[182:185], v0
	ds_read_b128 v[206:209], v0 offset:1024
	ds_read_b128 v[210:213], v0 offset:2048
	ds_read_b128 v[214:217], v0 offset:3072
	global_load_lds_dwordx4 v[186:187], off
	v_lshl_add_u64 v[186:187], v[218:219], 0, s[30:31]
	s_add_i32 m0, s12, 0x2000
	s_nop 0
	global_load_lds_dwordx4 v[186:187], off
	s_barrier
; #define PG8_STAGE(bufoff, gbase, voff) do { _Pragma("unroll") for (int _i = 0; _i < 2; ++_i) \
;         __builtin_amdgcn_global_load_lds((const unsigned*)((const char*)(gbase) + (voff)[_i]), (LAS unsigned*)(lds + (bufoff) + ldsw + _i * 8192), 16, 0, 0); } while (0)
; #define PG8_LDA(dst, b, h) do { _Pragma("unroll") for (int m = 0; m < 4; ++m) _Pragma("unroll") for (int k = 0; k < 2; ++k) dst[m][k] = *(const LAS bf16x8*)(lds + PG8_SA(b, h) + aoff + m * 2048 + k * 1024); } while (0)
; #define PG8_LDB(dst, b, h) do { _Pragma("unroll") for (int n = 0; n < 2; ++n) _Pragma("unroll") for (int k = 0; k < 2; ++k) dst[n][k] = *(const LAS bf16x8*)(lds + PG8_SB(b, h) + boff + n * 2048 + k * 1024); } while (0)
; #define PG8_MMA(ai, bj, At, Bt) do { __builtin_amdgcn_s_setprio(1); _Pragma("unroll") for (int m = 0; m < 4; ++m) _Pragma("unroll") for (int n = 0; n < 2; ++n) _Pragma("unroll") for (int k = 0; k < 2; ++k) \
;         acc[ai][bj][m][n] = __builtin_amdgcn_mfma_f32_16x16x32_bf16(Bt[n][k], At[m][k], acc[ai][bj][m][n], 0, 0, 0); __builtin_amdgcn_s_setprio(0); } while (0)
; #define PG8_WAIT_V(n) asm volatile("s_waitcnt vmcnt(" #n ")" ::: "memory")
; #define PG8_WAIT_L(n) asm volatile("s_waitcnt lgkmcnt(" #n ")" ::: "memory")
; #define PG8_BAR __builtin_amdgcn_s_barrier()
; #define PG8_SCHED __builtin_amdgcn_sched_barrier(0)
; __device__ __forceinline__ void gemm_phase(LAS unsigned char* lds, const Gemm g, const StaticOrder& S, const EpiAny& EA) {
;     ...
;             const char* a1 = cA + (size_t)(t + 1) * kstep;
;             const char* a2 = last ? nA : cA + (size_t)(t + 2) * kstep; const char* b2 = last ? nB : cB + (size_t)(t + 2) * kstep;
;             const char* a3 = a2 + kstep; const char* b3 = b2 + kstep;
;     ...
;             PG8_WAIT_L(8); PG8_BAR; PG8_WAIT_L(0); PG8_MMA(0, 0, At, B0); PG8_BAR; PG8_SCHED;
;             PG8_LDB(B1, 1, 1); PG8_STAGE(PG8_SB(1, 0), b3, voffB);
;             PG8_BAR; PG8_WAIT_L(0); PG8_MMA(0, 1, At, B1); PG8_BAR;
;             PG8_LDA(At, 1, 1); PG8_STAGE(PG8_SA(1, 0), a3, voffA);
;             PG8_BAR; PG8_WAIT_L(0); PG8_MMA(1, 0, At, B0); PG8_BAR; PG8_SCHED;
;             PG8_STAGE(PG8_SB(1, 1), b3 + hstep, voffB);
;             PG8_WAIT_V(6); PG8_BAR; PG8_MMA(1, 1, At, B1); PG8_BAR;
;         }
	s_waitcnt lgkmcnt(0)
	s_setprio 1
	s_waitcnt lgkmcnt(0)
	v_mfma_f32_16x16x32_bf16 v[94:97], v[182:185], v[150:153], v[94:97]
	v_mfma_f32_16x16x32_bf16 v[90:93], v[210:213], v[150:153], v[90:93]
	v_mfma_f32_16x16x32_bf16 v[86:89], v[182:185], v[158:161], v[86:89]
	v_mfma_f32_16x16x32_bf16 v[82:85], v[210:213], v[158:161], v[82:85]
	v_mfma_f32_16x16x32_bf16 v[78:81], v[182:185], v[166:169], v[78:81]
	v_mfma_f32_16x16x32_bf16 v[74:77], v[210:213], v[166:169], v[74:77]
	v_mfma_f32_16x16x32_bf16 v[70:73], v[182:185], v[174:177], v[70:73]
	v_mfma_f32_16x16x32_bf16 v[66:69], v[210:213], v[174:177], v[66:69]
	v_mfma_f32_16x16x32_bf16 v[94:97], v[206:209], v[154:157], v[94:97]
	v_mfma_f32_16x16x32_bf16 v[90:93], v[214:217], v[154:157], v[90:93]
	v_mfma_f32_16x16x32_bf16 v[86:89], v[206:209], v[162:165], v[86:89]
	v_mfma_f32_16x16x32_bf16 v[82:85], v[214:217], v[162:165], v[82:85]
	v_mfma_f32_16x16x32_bf16 v[78:81], v[206:209], v[170:173], v[78:81]
	v_mfma_f32_16x16x32_bf16 v[74:77], v[214:217], v[170:173], v[74:77]
	v_mfma_f32_16x16x32_bf16 v[70:73], v[206:209], v[178:181], v[70:73]
	v_mfma_f32_16x16x32_bf16 v[66:69], v[214:217], v[178:181], v[66:69]
	s_setprio 0
	s_mov_b32 m0, s80
	v_lshl_add_u64 v[186:187], v[220:221], 0, s[30:31]
	s_barrier
	ds_read_b128 v[150:153], v234 offset:49152
	ds_read_b128 v[154:157], v234 offset:50176
	ds_read_b128 v[158:161], v234 offset:51200
	ds_read_b128 v[162:165], v234 offset:52224
	ds_read_b128 v[166:169], v234 offset:53248
	ds_read_b128 v[170:173], v234 offset:54272
	ds_read_b128 v[174:177], v234 offset:55296
	ds_read_b128 v[178:181], v234 offset:56320
	global_load_lds_dwordx4 v[186:187], off
	v_lshl_add_u64 v[186:187], v[222:223], 0, s[30:31]
	s_mov_b32 m0, s81
	s_nop 0
	global_load_lds_dwordx4 v[186:187], off
	s_barrier
	s_waitcnt lgkmcnt(0)
	s_setprio 1
	s_waitcnt lgkmcnt(0)
	v_mfma_f32_16x16x32_bf16 v[62:65], v[134:137], v[150:153], v[62:65]
	v_mfma_f32_16x16x32_bf16 v[58:61], v[142:145], v[150:153], v[58:61]
	v_mfma_f32_16x16x32_bf16 v[54:57], v[134:137], v[158:161], v[54:57]
	v_mfma_f32_16x16x32_bf16 v[50:53], v[142:145], v[158:161], v[50:53]
	v_mfma_f32_16x16x32_bf16 v[46:49], v[134:137], v[166:169], v[46:49]
	v_mfma_f32_16x16x32_bf16 v[42:45], v[142:145], v[166:169], v[42:45]
	v_mfma_f32_16x16x32_bf16 v[38:41], v[134:137], v[174:177], v[38:41]
	v_mfma_f32_16x16x32_bf16 v[34:37], v[142:145], v[174:177], v[34:37]
	v_mfma_f32_16x16x32_bf16 v[62:65], v[138:141], v[154:157], v[62:65]
	v_mfma_f32_16x16x32_bf16 v[58:61], v[146:149], v[154:157], v[58:61]
	v_mfma_f32_16x16x32_bf16 v[54:57], v[138:141], v[162:165], v[54:57]
	v_mfma_f32_16x16x32_bf16 v[50:53], v[146:149], v[162:165], v[50:53]
	v_mfma_f32_16x16x32_bf16 v[46:49], v[138:141], v[170:173], v[46:49]
	v_mfma_f32_16x16x32_bf16 v[42:45], v[146:149], v[170:173], v[42:45]
	v_mfma_f32_16x16x32_bf16 v[38:41], v[138:141], v[178:181], v[38:41]
	v_mfma_f32_16x16x32_bf16 v[34:37], v[146:149], v[178:181], v[34:37]
	s_setprio 0
	s_barrier
	s_add_i32 s12, s24, s65
	v_lshl_add_u64 v[134:135], v[224:225], 0, s[30:31]
	s_mov_b32 m0, s12
	s_nop 0
	global_load_lds_dwordx4 v[134:135], off
	v_lshl_add_u64 v[134:135], v[238:239], 0, s[30:31]
	s_add_i32 m0, s12, 0x2000
	s_nop 0
	global_load_lds_dwordx4 v[134:135], off
	s_waitcnt vmcnt(6)
	s_barrier
	s_setprio 1
	v_mfma_f32_16x16x32_bf16 v[30:33], v[182:185], v[150:153], v[30:33]
	v_mfma_f32_16x16x32_bf16 v[26:29], v[210:213], v[150:153], v[26:29]
	v_mfma_f32_16x16x32_bf16 v[22:25], v[182:185], v[158:161], v[22:25]
	v_mfma_f32_16x16x32_bf16 v[18:21], v[210:213], v[158:161], v[18:21]
	v_mfma_f32_16x16x32_bf16 v[14:17], v[182:185], v[166:169], v[14:17]
	v_mfma_f32_16x16x32_bf16 v[10:13], v[210:213], v[166:169], v[10:13]
	v_mfma_f32_16x16x32_bf16 v[6:9], v[182:185], v[174:177], v[6:9]
	v_mfma_f32_16x16x32_bf16 v[2:5], v[210:213], v[174:177], v[2:5]
	v_mfma_f32_16x16x32_bf16 v[30:33], v[206:209], v[154:157], v[30:33]
	v_mfma_f32_16x16x32_bf16 v[26:29], v[214:217], v[154:157], v[26:29]
	v_mfma_f32_16x16x32_bf16 v[22:25], v[206:209], v[162:165], v[22:25]
	v_mfma_f32_16x16x32_bf16 v[18:21], v[214:217], v[162:165], v[18:21]
	v_mfma_f32_16x16x32_bf16 v[14:17], v[206:209], v[170:173], v[14:17]
	v_mfma_f32_16x16x32_bf16 v[10:13], v[214:217], v[170:173], v[10:13]
	v_mfma_f32_16x16x32_bf16 v[6:9], v[206:209], v[178:181], v[6:9]
	v_mfma_f32_16x16x32_bf16 v[2:5], v[214:217], v[178:181], v[2:5]
	s_setprio 0
	s_add_u32 s0, s0, 0x100
	s_addc_u32 s1, s1, 0
	v_lshl_add_u64 v[132:133], v[132:133], 0, s[56:57]
	v_lshl_add_u64 v[130:131], v[130:131], 0, s[56:57]
	s_mov_b32 s12, s13
	s_add_i32 s13, s12, 2
	s_add_u32 s24, s70, s0
	s_addc_u32 s25, s71, s1
	s_add_u32 s44, s28, s0
	s_addc_u32 s45, s29, s1
	s_add_i32 s46, 0, 0x10000
	v_add_u32_e32 v0, s46, v228
	s_cmp_ge_u32 s12, s78
	s_barrier
	s_cbranch_scc0 .LBB0_499
	s_lshl_b32 s0, s83, 10
	s_add_i32 s91, s0, 0
	s_add_i32 s91, s91, 0x21000
	s_lshl_b32 s48, s72, 8
	s_cmp_lt_i32 s35, 1
	s_mov_b64 s[0:1], -1
	s_cbranch_scc0 .LBB0_503
	s_andn2_b64 vcc, exec, s[0:1]
	s_cbranch_vccz .LBB0_651
